# m23 with s_sleep removed from the 37 grid-barrier / LN-seam spin loops (tighter polling)
# baseline (speedup 1.0000x reference)
; __device__ __forceinline__ unsigned xb_ld(unsigned* p)              { return __hip_atomic_load(p, __ATOMIC_RELAXED, __HIP_MEMORY_SCOPE_AGENT); }
; __device__ __forceinline__ void xcd_barrier_complete(unsigned* bar, unsigned x, unsigned& nloc, unsigned& nx) {
;     const unsigned G = gridDim.x * gridDim.y * gridDim.z;
;     unsigned sum, cnt, mine, sp = 0u;
;     for (;;) {
;         sum = 0u; cnt = 0u; mine = 0u;
; #pragma unroll
;         for (unsigned j = 0; j < 16; ++j) { const unsigned c = xb_ld(&bar[XB_XCNT(j)]); sum += c; cnt += (c > 0u) ? 1u : 0u; mine = (j == x) ? c : mine; }
;         if (sum == G) break;
;         __builtin_amdgcn_s_sleep(1);
;         if ((++sp & 255u) == 0u) { if (xb_ld(&bar[XB_TMO])) break; if (sp > XB_SPIN_CAP) { atomicAdd(&bar[XB_TMO], 1u); break; } }
;     }
.LBB11_166:
	global_load_dword v16, v17, s[8:9] sc1
	global_load_dword v1, v17, s[10:11] sc1
	global_load_dword v2, v17, s[12:13] sc1
	global_load_dword v3, v17, s[14:15] sc1
	global_load_dword v4, v17, s[16:17] sc1
	global_load_dword v5, v17, s[18:19] sc1
	global_load_dword v6, v17, s[20:21] sc1
	global_load_dword v7, v17, s[22:23] sc1
	global_load_dword v8, v17, s[24:25] sc1
	global_load_dword v9, v17, s[26:27] sc1
	global_load_dword v10, v17, s[28:29] sc1
	global_load_dword v11, v17, s[30:31] sc1
	global_load_dword v12, v17, s[34:35] sc1
	global_load_dword v13, v17, s[36:37] sc1
	global_load_dword v14, v17, s[38:39] sc1
	global_load_dword v15, v17, s[40:41] sc1
	s_mov_b64 s[42:43], -1
	s_mov_b64 s[44:45], -1
	s_waitcnt vmcnt(14)
	v_add_u32_e32 v18, v1, v16
	s_waitcnt vmcnt(13)
	v_add_u32_e32 v18, v18, v2
	s_waitcnt vmcnt(12)
	v_add_u32_e32 v18, v18, v3
	s_waitcnt vmcnt(11)
	v_add_u32_e32 v18, v18, v4
	s_waitcnt vmcnt(10)
	v_add_u32_e32 v18, v18, v5
	s_waitcnt vmcnt(9)
	v_add_u32_e32 v18, v18, v6
	s_waitcnt vmcnt(8)
	v_add_u32_e32 v18, v18, v7
	s_waitcnt vmcnt(7)
	v_add_u32_e32 v18, v18, v8
	s_waitcnt vmcnt(6)
	v_add_u32_e32 v18, v18, v9
	s_waitcnt vmcnt(5)
	v_add_u32_e32 v18, v18, v10
	s_waitcnt vmcnt(4)
	v_add_u32_e32 v18, v18, v11
	s_waitcnt vmcnt(3)
	v_add_u32_e32 v18, v18, v12
	s_waitcnt vmcnt(2)
	v_add_u32_e32 v18, v18, v13
	s_waitcnt vmcnt(1)
	v_add_u32_e32 v18, v18, v14
	s_waitcnt vmcnt(0)
	v_add_u32_e32 v18, v18, v15
	v_cmp_eq_u32_e32 vcc, s48, v18
	s_cbranch_vccnz .LBB11_165
	s_and_b32 s42, s49, 0xff
	s_cmp_eq_u32 s42, 0
	s_mov_b64 s[42:43], -1
	s_mov_b64 s[46:47], -1
	s_nop 0
	s_cbranch_scc0 .LBB11_170
	global_load_dword v18, v17, s[6:7] sc1
	s_waitcnt vmcnt(0)
	v_cmp_eq_u32_e32 vcc, 0, v18
	s_cbranch_vccnz .LBB11_172
	s_mov_b64 s[46:47], 0

; __device__ __forceinline__ unsigned xb_ld(unsigned* p)              { return __hip_atomic_load(p, __ATOMIC_RELAXED, __HIP_MEMORY_SCOPE_AGENT); }
; __device__ __forceinline__ unsigned xb_add(unsigned* p, unsigned v) { return __hip_atomic_fetch_add(p, v, __ATOMIC_RELAXED, __HIP_MEMORY_SCOPE_AGENT); }
; #define XB_SPIN(cond, bar) do { unsigned _sp = 0; while (cond) { __builtin_amdgcn_s_sleep(1); \
;     if ((++_sp & 255u) == 0u) { if (xb_ld(&(bar)[XB_TMO])) break; if (_sp > XB_SPIN_CAP) { atomicAdd(&(bar)[XB_TMO], 1u); break; } } } } while (0)
; __device__ __forceinline__ void xcd_barrier(const XcdBarrier& b) {
;     ...
;             else XB_SPIN(xb_ld(&bar[XB_TOPGEN]) == tg, bar);
;             __builtin_amdgcn_fence(__ATOMIC_ACQUIRE, "agent");
;             xb_add(&bar[XB_XGEN(b.x)], 1u);
;             asm volatile("s_waitcnt vmcnt(0)" ::: "memory");
;         } else {
;             XB_SPIN(xb_ld(&bar[XB_XGEN(b.x)]) == gen, bar);
.LBB11_184:
	s_and_b32 s20, s24, 0xff
	s_mov_b64 s[18:19], -1
	s_cmp_lg_u32 s20, 0
	s_mov_b64 s[22:23], -1
	s_nop 0
	s_cbranch_scc1 .LBB11_187
	global_load_dword v3, v1, s[6:7] sc1
	s_waitcnt vmcnt(0)
	v_cmp_eq_u32_e32 vcc, 0, v3
	s_cbranch_vccnz .LBB11_189
	s_mov_b64 s[22:23], 0
	s_mov_b64 s[20:21], -1

; __device__ __forceinline__ unsigned xb_ld(unsigned* p)              { return __hip_atomic_load(p, __ATOMIC_RELAXED, __HIP_MEMORY_SCOPE_AGENT); }
; __device__ __forceinline__ unsigned xb_add(unsigned* p, unsigned v) { return __hip_atomic_fetch_add(p, v, __ATOMIC_RELAXED, __HIP_MEMORY_SCOPE_AGENT); }
; #define XB_SPIN(cond, bar) do { unsigned _sp = 0; while (cond) { __builtin_amdgcn_s_sleep(1); \
;     if ((++_sp & 255u) == 0u) { if (xb_ld(&(bar)[XB_TMO])) break; if (_sp > XB_SPIN_CAP) { atomicAdd(&(bar)[XB_TMO], 1u); break; } } } } while (0)
; __device__ __forceinline__ void xcd_barrier(const XcdBarrier& b) {
;     ...
;             else XB_SPIN(xb_ld(&bar[XB_TOPGEN]) == tg, bar);
;             __builtin_amdgcn_fence(__ATOMIC_ACQUIRE, "agent");
;             xb_add(&bar[XB_XGEN(b.x)], 1u);
;             asm volatile("s_waitcnt vmcnt(0)" ::: "memory");
;         } else {
;             XB_SPIN(xb_ld(&bar[XB_XGEN(b.x)]) == gen, bar);
.LBB11_201:
	s_and_b32 s20, s26, 0xff
	s_cmp_lg_u32 s20, 0
	s_mov_b64 s[22:23], -1
	s_nop 0
	s_cbranch_scc1 .LBB11_204
	global_load_dword v2, v1, s[6:7] sc1
	s_waitcnt vmcnt(0)
	v_cmp_eq_u32_e32 vcc, 0, v2
	s_cbranch_vccnz .LBB11_206
	s_mov_b64 s[22:23], 0
	s_mov_b64 s[20:21], -1

; __device__ __forceinline__ unsigned xb_ld(unsigned* p)              { return __hip_atomic_load(p, __ATOMIC_RELAXED, __HIP_MEMORY_SCOPE_AGENT); }
; __device__ __forceinline__ void xcd_barrier_complete(unsigned* bar, unsigned x, unsigned& nloc, unsigned& nx) {
;     const unsigned G = gridDim.x * gridDim.y * gridDim.z;
;     unsigned sum, cnt, mine, sp = 0u;
;     for (;;) {
;         sum = 0u; cnt = 0u; mine = 0u;
; #pragma unroll
;         for (unsigned j = 0; j < 16; ++j) { const unsigned c = xb_ld(&bar[XB_XCNT(j)]); sum += c; cnt += (c > 0u) ? 1u : 0u; mine = (j == x) ? c : mine; }
;         if (sum == G) break;
;         __builtin_amdgcn_s_sleep(1);
;         if ((++sp & 255u) == 0u) { if (xb_ld(&bar[XB_TMO])) break; if (sp > XB_SPIN_CAP) { atomicAdd(&bar[XB_TMO], 1u); break; } }
;     }
.LBB11_367:
	v_readlane_b32 s6, v249, 45
	v_readlane_b32 s7, v249, 46
	s_mov_b64 s[8:9], -1
	s_nop 3
	global_load_dword v1, v3, s[6:7] sc1
	v_readlane_b32 s6, v249, 47
	v_readlane_b32 s7, v249, 48
	s_nop 4
	global_load_dword v2, v3, s[6:7] sc1
	v_readlane_b32 s6, v249, 49
	v_readlane_b32 s7, v249, 50
	s_waitcnt vmcnt(0)
	v_add_u32_e32 v18, v2, v1
	s_nop 2
	global_load_dword v4, v3, s[6:7] sc1
	v_readlane_b32 s6, v249, 51
	v_readlane_b32 s7, v249, 52
	s_waitcnt vmcnt(0)
	v_add_u32_e32 v18, v18, v4
	s_nop 2
	global_load_dword v5, v3, s[6:7] sc1
	v_readlane_b32 s6, v249, 53
	v_readlane_b32 s7, v249, 54
	s_waitcnt vmcnt(0)
	v_add_u32_e32 v18, v18, v5
	s_nop 2
	global_load_dword v6, v3, s[6:7] sc1
	v_readlane_b32 s6, v249, 55
	v_readlane_b32 s7, v249, 56
	s_waitcnt vmcnt(0)
	v_add_u32_e32 v18, v18, v6
	s_nop 2
	global_load_dword v7, v3, s[6:7] sc1
	v_readlane_b32 s6, v249, 57
	v_readlane_b32 s7, v249, 58
	s_waitcnt vmcnt(0)
	v_add_u32_e32 v18, v18, v7
	s_nop 2
	global_load_dword v8, v3, s[6:7] sc1
	v_readlane_b32 s6, v249, 59
	v_readlane_b32 s7, v249, 60
	s_waitcnt vmcnt(0)
	v_add_u32_e32 v18, v18, v8
	s_nop 2
	global_load_dword v9, v3, s[6:7] sc1
	v_readlane_b32 s6, v249, 61
	v_readlane_b32 s7, v249, 62
	s_waitcnt vmcnt(0)
	v_add_u32_e32 v18, v18, v9
	s_nop 2
	global_load_dword v10, v3, s[6:7] sc1
	v_readlane_b32 s6, v249, 63
	v_readlane_b32 s7, v250, 0
	s_waitcnt vmcnt(0)
	v_add_u32_e32 v18, v18, v10
	s_nop 2
	global_load_dword v11, v3, s[6:7] sc1
	v_readlane_b32 s6, v250, 1
	v_readlane_b32 s7, v250, 2
	s_waitcnt vmcnt(0)
	v_add_u32_e32 v18, v18, v11
	s_nop 2
	global_load_dword v12, v3, s[6:7] sc1
	v_readlane_b32 s6, v250, 3
	v_readlane_b32 s7, v250, 4
	s_waitcnt vmcnt(0)
	v_add_u32_e32 v18, v18, v12
	s_nop 2
	global_load_dword v13, v3, s[6:7] sc1
	v_readlane_b32 s6, v250, 5
	v_readlane_b32 s7, v250, 6
	s_waitcnt vmcnt(0)
	v_add_u32_e32 v18, v18, v13
	s_nop 2
	global_load_dword v14, v3, s[6:7] sc1
	v_readlane_b32 s6, v250, 7
	v_readlane_b32 s7, v250, 8
	s_waitcnt vmcnt(0)
	v_add_u32_e32 v18, v18, v14
	s_nop 2
	global_load_dword v15, v3, s[6:7] sc1
	v_readlane_b32 s6, v250, 9
	v_readlane_b32 s7, v250, 10
	s_waitcnt vmcnt(0)
	v_add_u32_e32 v18, v18, v15
	s_nop 2
	global_load_dword v16, v3, s[6:7] sc1
	v_readlane_b32 s6, v250, 11
	v_readlane_b32 s7, v250, 12
	s_waitcnt vmcnt(0)
	v_add_u32_e32 v18, v18, v16
	s_nop 2
	global_load_dword v17, v3, s[6:7] sc1
	s_mov_b64 s[6:7], -1
	s_waitcnt vmcnt(0)
	v_add_u32_e32 v18, v18, v17
	v_cmp_eq_u32_e32 vcc, s1, v18
	s_cbranch_vccnz .LBB11_366
	s_and_b32 s6, s12, 0xff
	s_cmp_eq_u32 s6, 0
	s_mov_b64 s[6:7], -1
	s_mov_b64 s[10:11], -1
	s_nop 0
	s_cbranch_scc0 .LBB11_371
	v_readlane_b32 s6, v249, 43
	v_readlane_b32 s7, v249, 44
	s_nop 4
	global_load_dword v18, v3, s[6:7] sc1
	s_waitcnt vmcnt(0)
	v_cmp_eq_u32_e32 vcc, 0, v18
	s_cbranch_vccnz .LBB11_373
	s_mov_b64 s[10:11], 0
	s_mov_b64 s[6:7], -1

; __device__ __forceinline__ unsigned xb_ld(unsigned* p)              { return __hip_atomic_load(p, __ATOMIC_RELAXED, __HIP_MEMORY_SCOPE_AGENT); }
; __device__ __forceinline__ void xcd_barrier_complete(unsigned* bar, unsigned x, unsigned& nloc, unsigned& nx) {
;     const unsigned G = gridDim.x * gridDim.y * gridDim.z;
;     unsigned sum, cnt, mine, sp = 0u;
;     for (;;) {
;         sum = 0u; cnt = 0u; mine = 0u;
; #pragma unroll
;         for (unsigned j = 0; j < 16; ++j) { const unsigned c = xb_ld(&bar[XB_XCNT(j)]); sum += c; cnt += (c > 0u) ? 1u : 0u; mine = (j == x) ? c : mine; }
;         if (sum == G) break;
;         __builtin_amdgcn_s_sleep(1);
;         if ((++sp & 255u) == 0u) { if (xb_ld(&bar[XB_TMO])) break; if (sp > XB_SPIN_CAP) { atomicAdd(&bar[XB_TMO], 1u); break; } }
;     }
.LBB11_381:
	v_readlane_b32 s4, v249, 45
	v_readlane_b32 s5, v249, 46
	s_mov_b64 s[8:9], -1
	s_nop 3
	global_load_dword v1, v3, s[4:5] sc1
	v_readlane_b32 s4, v249, 47
	v_readlane_b32 s5, v249, 48
	s_nop 4
	global_load_dword v2, v3, s[4:5] sc1
	v_readlane_b32 s4, v249, 49
	v_readlane_b32 s5, v249, 50
	s_waitcnt vmcnt(0)
	v_add_u32_e32 v18, v2, v1
	s_nop 2
	global_load_dword v4, v3, s[4:5] sc1
	v_readlane_b32 s4, v249, 51
	v_readlane_b32 s5, v249, 52
	s_waitcnt vmcnt(0)
	v_add_u32_e32 v18, v18, v4
	s_nop 2
	global_load_dword v5, v3, s[4:5] sc1
	v_readlane_b32 s4, v249, 53
	v_readlane_b32 s5, v249, 54
	s_waitcnt vmcnt(0)
	v_add_u32_e32 v18, v18, v5
	s_nop 2
	global_load_dword v6, v3, s[4:5] sc1
	v_readlane_b32 s4, v249, 55
	v_readlane_b32 s5, v249, 56
	s_waitcnt vmcnt(0)
	v_add_u32_e32 v18, v18, v6
	s_nop 2
	global_load_dword v7, v3, s[4:5] sc1
	v_readlane_b32 s4, v249, 57
	v_readlane_b32 s5, v249, 58
	s_waitcnt vmcnt(0)
	v_add_u32_e32 v18, v18, v7
	s_nop 2
	global_load_dword v8, v3, s[4:5] sc1
	v_readlane_b32 s4, v249, 59
	v_readlane_b32 s5, v249, 60
	s_waitcnt vmcnt(0)
	v_add_u32_e32 v18, v18, v8
	s_nop 2
	global_load_dword v9, v3, s[4:5] sc1
	v_readlane_b32 s4, v249, 61
	v_readlane_b32 s5, v249, 62
	s_waitcnt vmcnt(0)
	v_add_u32_e32 v18, v18, v9
	s_nop 2
	global_load_dword v10, v3, s[4:5] sc1
	v_readlane_b32 s4, v249, 63
	v_readlane_b32 s5, v250, 0
	s_waitcnt vmcnt(0)
	v_add_u32_e32 v18, v18, v10
	s_nop 2
	global_load_dword v11, v3, s[4:5] sc1
	v_readlane_b32 s4, v250, 1
	v_readlane_b32 s5, v250, 2
	s_waitcnt vmcnt(0)
	v_add_u32_e32 v18, v18, v11
	s_nop 2
	global_load_dword v12, v3, s[4:5] sc1
	v_readlane_b32 s4, v250, 3
	v_readlane_b32 s5, v250, 4
	s_waitcnt vmcnt(0)
	v_add_u32_e32 v18, v18, v12
	s_nop 2
	global_load_dword v13, v3, s[4:5] sc1
	v_readlane_b32 s4, v250, 5
	v_readlane_b32 s5, v250, 6
	s_waitcnt vmcnt(0)
	v_add_u32_e32 v18, v18, v13
	s_nop 2
	global_load_dword v14, v3, s[4:5] sc1
	v_readlane_b32 s4, v250, 7
	v_readlane_b32 s5, v250, 8
	s_waitcnt vmcnt(0)
	v_add_u32_e32 v18, v18, v14
	s_nop 2
	global_load_dword v15, v3, s[4:5] sc1
	v_readlane_b32 s4, v250, 9
	v_readlane_b32 s5, v250, 10
	s_waitcnt vmcnt(0)
	v_add_u32_e32 v18, v18, v15
	s_nop 2
	global_load_dword v16, v3, s[4:5] sc1
	v_readlane_b32 s4, v250, 11
	v_readlane_b32 s5, v250, 12
	s_waitcnt vmcnt(0)
	v_add_u32_e32 v18, v18, v16
	s_nop 2
	global_load_dword v17, v3, s[4:5] sc1
	s_mov_b64 s[4:5], -1
	s_waitcnt vmcnt(0)
	v_add_u32_e32 v18, v18, v17
	v_cmp_eq_u32_e32 vcc, s1, v18
	s_cbranch_vccnz .LBB11_380
	s_and_b32 s4, s12, 0xff
	s_cmp_eq_u32 s4, 0
	s_mov_b64 s[4:5], -1
	s_mov_b64 s[10:11], -1
	s_nop 0
	s_cbranch_scc0 .LBB11_385
	v_readlane_b32 s4, v249, 43
	v_readlane_b32 s5, v249, 44
	s_nop 4
	global_load_dword v18, v3, s[4:5] sc1
	s_waitcnt vmcnt(0)
	v_cmp_eq_u32_e32 vcc, 0, v18
	s_cbranch_vccnz .LBB11_387
	s_mov_b64 s[10:11], 0
	s_mov_b64 s[4:5], -1

; __device__ __forceinline__ unsigned xb_ld(unsigned* p)              { return __hip_atomic_load(p, __ATOMIC_RELAXED, __HIP_MEMORY_SCOPE_AGENT); }
; __device__ __forceinline__ unsigned xb_add(unsigned* p, unsigned v) { return __hip_atomic_fetch_add(p, v, __ATOMIC_RELAXED, __HIP_MEMORY_SCOPE_AGENT); }
; #define XB_SPIN(cond, bar) do { unsigned _sp = 0; while (cond) { __builtin_amdgcn_s_sleep(1); \
;     if ((++_sp & 255u) == 0u) { if (xb_ld(&(bar)[XB_TMO])) break; if (_sp > XB_SPIN_CAP) { atomicAdd(&(bar)[XB_TMO], 1u); break; } } } } while (0)
; __device__ __forceinline__ void xcd_barrier(const XcdBarrier& b) {
;     ...
;             else XB_SPIN(xb_ld(&bar[XB_TOPGEN]) == tg, bar);
;             __builtin_amdgcn_fence(__ATOMIC_ACQUIRE, "agent");
;             xb_add(&bar[XB_XGEN(b.x)], 1u);
;             asm volatile("s_waitcnt vmcnt(0)" ::: "memory");
;         } else {
;             XB_SPIN(xb_ld(&bar[XB_XGEN(b.x)]) == gen, bar);
.LBB11_399:
	s_and_b32 s16, s1, 0xff
	s_mov_b64 s[14:15], -1
	s_cmp_lg_u32 s16, 0
	s_mov_b64 s[18:19], -1
	s_nop 0
	s_cbranch_scc1 .LBB11_402
	v_readlane_b32 s16, v249, 43
	v_readlane_b32 s17, v249, 44
	s_nop 4
	global_load_dword v2, v3, s[16:17] sc1
	s_waitcnt vmcnt(0)
	v_cmp_eq_u32_e32 vcc, 0, v2
	s_cbranch_vccnz .LBB11_404
	s_mov_b64 s[18:19], 0
	s_mov_b64 s[16:17], -1

; __device__ __forceinline__ unsigned xb_ld(unsigned* p)              { return __hip_atomic_load(p, __ATOMIC_RELAXED, __HIP_MEMORY_SCOPE_AGENT); }
; __device__ __forceinline__ void xcd_barrier_complete(unsigned* bar, unsigned x, unsigned& nloc, unsigned& nx) {
;     const unsigned G = gridDim.x * gridDim.y * gridDim.z;
;     unsigned sum, cnt, mine, sp = 0u;
;     for (;;) {
;         sum = 0u; cnt = 0u; mine = 0u;
; #pragma unroll
;         for (unsigned j = 0; j < 16; ++j) { const unsigned c = xb_ld(&bar[XB_XCNT(j)]); sum += c; cnt += (c > 0u) ? 1u : 0u; mine = (j == x) ? c : mine; }
;         if (sum == G) break;
;         __builtin_amdgcn_s_sleep(1);
;         if ((++sp & 255u) == 0u) { if (xb_ld(&bar[XB_TMO])) break; if (sp > XB_SPIN_CAP) { atomicAdd(&bar[XB_TMO], 1u); break; } }
;     }
.LBB11_855:
	v_readlane_b32 s4, v249, 45
	v_readlane_b32 s5, v249, 46
	s_mov_b64 s[6:7], -1
	s_nop 3
	global_load_dword v1, v3, s[4:5] sc1
	v_readlane_b32 s4, v249, 47
	v_readlane_b32 s5, v249, 48
	s_nop 4
	global_load_dword v2, v3, s[4:5] sc1
	v_readlane_b32 s4, v249, 49
	v_readlane_b32 s5, v249, 50
	s_waitcnt vmcnt(0)
	v_add_u32_e32 v18, v2, v1
	s_nop 2
	global_load_dword v4, v3, s[4:5] sc1
	v_readlane_b32 s4, v249, 51
	v_readlane_b32 s5, v249, 52
	s_waitcnt vmcnt(0)
	v_add_u32_e32 v18, v18, v4
	s_nop 2
	global_load_dword v5, v3, s[4:5] sc1
	v_readlane_b32 s4, v249, 53
	v_readlane_b32 s5, v249, 54
	s_waitcnt vmcnt(0)
	v_add_u32_e32 v18, v18, v5
	s_nop 2
	global_load_dword v6, v3, s[4:5] sc1
	v_readlane_b32 s4, v249, 55
	v_readlane_b32 s5, v249, 56
	s_waitcnt vmcnt(0)
	v_add_u32_e32 v18, v18, v6
	s_nop 2
	global_load_dword v7, v3, s[4:5] sc1
	v_readlane_b32 s4, v249, 57
	v_readlane_b32 s5, v249, 58
	s_waitcnt vmcnt(0)
	v_add_u32_e32 v18, v18, v7
	s_nop 2
	global_load_dword v8, v3, s[4:5] sc1
	v_readlane_b32 s4, v249, 59
	v_readlane_b32 s5, v249, 60
	s_waitcnt vmcnt(0)
	v_add_u32_e32 v18, v18, v8
	s_nop 2
	global_load_dword v9, v3, s[4:5] sc1
	v_readlane_b32 s4, v249, 61
	v_readlane_b32 s5, v249, 62
	s_waitcnt vmcnt(0)
	v_add_u32_e32 v18, v18, v9
	s_nop 2
	global_load_dword v10, v3, s[4:5] sc1
	v_readlane_b32 s4, v249, 63
	v_readlane_b32 s5, v250, 0
	s_waitcnt vmcnt(0)
	v_add_u32_e32 v18, v18, v10
	s_nop 2
	global_load_dword v11, v3, s[4:5] sc1
	v_readlane_b32 s4, v250, 1
	v_readlane_b32 s5, v250, 2
	s_waitcnt vmcnt(0)
	v_add_u32_e32 v18, v18, v11
	s_nop 2
	global_load_dword v12, v3, s[4:5] sc1
	v_readlane_b32 s4, v250, 3
	v_readlane_b32 s5, v250, 4
	s_waitcnt vmcnt(0)
	v_add_u32_e32 v18, v18, v12
	s_nop 2
	global_load_dword v13, v3, s[4:5] sc1
	v_readlane_b32 s4, v250, 5
	v_readlane_b32 s5, v250, 6
	s_waitcnt vmcnt(0)
	v_add_u32_e32 v18, v18, v13
	s_nop 2
	global_load_dword v14, v3, s[4:5] sc1
	v_readlane_b32 s4, v250, 7
	v_readlane_b32 s5, v250, 8
	s_waitcnt vmcnt(0)
	v_add_u32_e32 v18, v18, v14
	s_nop 2
	global_load_dword v15, v3, s[4:5] sc1
	v_readlane_b32 s4, v250, 9
	v_readlane_b32 s5, v250, 10
	s_waitcnt vmcnt(0)
	v_add_u32_e32 v18, v18, v15
	s_nop 2
	global_load_dword v16, v3, s[4:5] sc1
	v_readlane_b32 s4, v250, 11
	v_readlane_b32 s5, v250, 12
	s_waitcnt vmcnt(0)
	v_add_u32_e32 v18, v18, v16
	s_nop 2
	global_load_dword v17, v3, s[4:5] sc1
	s_mov_b64 s[4:5], -1
	s_waitcnt vmcnt(0)
	v_add_u32_e32 v18, v18, v17
	v_cmp_eq_u32_e32 vcc, s1, v18
	s_cbranch_vccnz .LBB11_854
	s_and_b32 s4, s10, 0xff
	s_cmp_eq_u32 s4, 0
	s_mov_b64 s[4:5], -1
	s_mov_b64 s[8:9], -1
	s_nop 0
	s_cbranch_scc0 .LBB11_859
	v_readlane_b32 s4, v249, 43
	v_readlane_b32 s5, v249, 44
	s_nop 4
	global_load_dword v18, v3, s[4:5] sc1
	s_waitcnt vmcnt(0)
	v_cmp_eq_u32_e32 vcc, 0, v18
	s_cbranch_vccnz .LBB11_861
	s_mov_b64 s[8:9], 0
	s_mov_b64 s[4:5], -1

; __device__ __forceinline__ unsigned xb_ld(unsigned* p)              { return __hip_atomic_load(p, __ATOMIC_RELAXED, __HIP_MEMORY_SCOPE_AGENT); }
; __device__ __forceinline__ unsigned xb_add(unsigned* p, unsigned v) { return __hip_atomic_fetch_add(p, v, __ATOMIC_RELAXED, __HIP_MEMORY_SCOPE_AGENT); }
; #define XB_SPIN(cond, bar) do { unsigned _sp = 0; while (cond) { __builtin_amdgcn_s_sleep(1); \
;     if ((++_sp & 255u) == 0u) { if (xb_ld(&(bar)[XB_TMO])) break; if (_sp > XB_SPIN_CAP) { atomicAdd(&(bar)[XB_TMO], 1u); break; } } } } while (0)
; __device__ __forceinline__ void xcd_barrier(const XcdBarrier& b) {
;     ...
;             else XB_SPIN(xb_ld(&bar[XB_TOPGEN]) == tg, bar);
;             __builtin_amdgcn_fence(__ATOMIC_ACQUIRE, "agent");
;             xb_add(&bar[XB_XGEN(b.x)], 1u);
;             asm volatile("s_waitcnt vmcnt(0)" ::: "memory");
;         } else {
;             XB_SPIN(xb_ld(&bar[XB_XGEN(b.x)]) == gen, bar);
.LBB11_873:
	s_and_b32 s14, s1, 0xff
	s_mov_b64 s[12:13], -1
	s_cmp_lg_u32 s14, 0
	s_mov_b64 s[16:17], -1
	s_nop 0
	s_cbranch_scc1 .LBB11_876
	v_readlane_b32 s14, v249, 43
	v_readlane_b32 s15, v249, 44
	s_nop 4
	global_load_dword v2, v3, s[14:15] sc1
	s_waitcnt vmcnt(0)
	v_cmp_eq_u32_e32 vcc, 0, v2
	s_cbranch_vccnz .LBB11_878
	s_mov_b64 s[16:17], 0
	s_mov_b64 s[14:15], -1

; __device__ __forceinline__ unsigned xb_ld(unsigned* p)              { return __hip_atomic_load(p, __ATOMIC_RELAXED, __HIP_MEMORY_SCOPE_AGENT); }
; __device__ __forceinline__ void xcd_barrier_complete(unsigned* bar, unsigned x, unsigned& nloc, unsigned& nx) {
;     const unsigned G = gridDim.x * gridDim.y * gridDim.z;
;     unsigned sum, cnt, mine, sp = 0u;
;     for (;;) {
;         sum = 0u; cnt = 0u; mine = 0u;
; #pragma unroll
;         for (unsigned j = 0; j < 16; ++j) { const unsigned c = xb_ld(&bar[XB_XCNT(j)]); sum += c; cnt += (c > 0u) ? 1u : 0u; mine = (j == x) ? c : mine; }
;         if (sum == G) break;
;         __builtin_amdgcn_s_sleep(1);
;         if ((++sp & 255u) == 0u) { if (xb_ld(&bar[XB_TMO])) break; if (sp > XB_SPIN_CAP) { atomicAdd(&bar[XB_TMO], 1u); break; } }
;     }
.LBB11_1674:
	v_readlane_b32 s4, v249, 45
	v_readlane_b32 s5, v249, 46
	s_mov_b64 s[14:15], -1
	s_nop 3
	global_load_dword v1, v3, s[4:5] sc1
	v_readlane_b32 s4, v249, 47
	v_readlane_b32 s5, v249, 48
	s_nop 4
	global_load_dword v2, v3, s[4:5] sc1
	v_readlane_b32 s4, v249, 49
	v_readlane_b32 s5, v249, 50
	s_waitcnt vmcnt(0)
	v_add_u32_e32 v18, v2, v1
	s_nop 2
	global_load_dword v4, v3, s[4:5] sc1
	v_readlane_b32 s4, v249, 51
	v_readlane_b32 s5, v249, 52
	s_waitcnt vmcnt(0)
	v_add_u32_e32 v18, v18, v4
	s_nop 2
	global_load_dword v5, v3, s[4:5] sc1
	v_readlane_b32 s4, v249, 53
	v_readlane_b32 s5, v249, 54
	s_waitcnt vmcnt(0)
	v_add_u32_e32 v18, v18, v5
	s_nop 2
	global_load_dword v6, v3, s[4:5] sc1
	v_readlane_b32 s4, v249, 55
	v_readlane_b32 s5, v249, 56
	s_waitcnt vmcnt(0)
	v_add_u32_e32 v18, v18, v6
	s_nop 2
	global_load_dword v7, v3, s[4:5] sc1
	v_readlane_b32 s4, v249, 57
	v_readlane_b32 s5, v249, 58
	s_waitcnt vmcnt(0)
	v_add_u32_e32 v18, v18, v7
	s_nop 2
	global_load_dword v8, v3, s[4:5] sc1
	v_readlane_b32 s4, v249, 59
	v_readlane_b32 s5, v249, 60
	s_waitcnt vmcnt(0)
	v_add_u32_e32 v18, v18, v8
	s_nop 2
	global_load_dword v9, v3, s[4:5] sc1
	v_readlane_b32 s4, v249, 61
	v_readlane_b32 s5, v249, 62
	s_waitcnt vmcnt(0)
	v_add_u32_e32 v18, v18, v9
	s_nop 2
	global_load_dword v10, v3, s[4:5] sc1
	v_readlane_b32 s4, v249, 63
	v_readlane_b32 s5, v250, 0
	s_waitcnt vmcnt(0)
	v_add_u32_e32 v18, v18, v10
	s_nop 2
	global_load_dword v11, v3, s[4:5] sc1
	v_readlane_b32 s4, v250, 1
	v_readlane_b32 s5, v250, 2
	s_waitcnt vmcnt(0)
	v_add_u32_e32 v18, v18, v11
	s_nop 2
	global_load_dword v12, v3, s[4:5] sc1
	v_readlane_b32 s4, v250, 3
	v_readlane_b32 s5, v250, 4
	s_waitcnt vmcnt(0)
	v_add_u32_e32 v18, v18, v12
	s_nop 2
	global_load_dword v13, v3, s[4:5] sc1
	v_readlane_b32 s4, v250, 5
	v_readlane_b32 s5, v250, 6
	s_waitcnt vmcnt(0)
	v_add_u32_e32 v18, v18, v13
	s_nop 2
	global_load_dword v14, v3, s[4:5] sc1
	v_readlane_b32 s4, v250, 7
	v_readlane_b32 s5, v250, 8
	s_waitcnt vmcnt(0)
	v_add_u32_e32 v18, v18, v14
	s_nop 2
	global_load_dword v15, v3, s[4:5] sc1
	v_readlane_b32 s4, v250, 9
	v_readlane_b32 s5, v250, 10
	s_waitcnt vmcnt(0)
	v_add_u32_e32 v18, v18, v15
	s_nop 2
	global_load_dword v16, v3, s[4:5] sc1
	v_readlane_b32 s4, v250, 11
	v_readlane_b32 s5, v250, 12
	s_waitcnt vmcnt(0)
	v_add_u32_e32 v18, v18, v16
	s_nop 2
	global_load_dword v17, v3, s[4:5] sc1
	s_mov_b64 s[4:5], -1
	s_waitcnt vmcnt(0)
	v_add_u32_e32 v18, v18, v17
	v_cmp_eq_u32_e32 vcc, s1, v18
	s_cbranch_vccnz .LBB11_1673
	s_and_b32 s4, s13, 0xff
	s_cmp_eq_u32 s4, 0
	s_mov_b64 s[4:5], -1
	s_mov_b64 s[16:17], -1
	s_nop 0
	s_cbranch_scc0 .LBB11_1678
	v_readlane_b32 s4, v249, 43
	v_readlane_b32 s5, v249, 44
	s_nop 4
	global_load_dword v18, v3, s[4:5] sc1
	s_waitcnt vmcnt(0)
	v_cmp_eq_u32_e32 vcc, 0, v18
	s_cbranch_vccnz .LBB11_1680
	s_mov_b64 s[16:17], 0
	s_mov_b64 s[4:5], -1

; __device__ __forceinline__ unsigned xb_ld(unsigned* p)              { return __hip_atomic_load(p, __ATOMIC_RELAXED, __HIP_MEMORY_SCOPE_AGENT); }
; __device__ __forceinline__ unsigned xb_add(unsigned* p, unsigned v) { return __hip_atomic_fetch_add(p, v, __ATOMIC_RELAXED, __HIP_MEMORY_SCOPE_AGENT); }
; #define XB_SPIN(cond, bar) do { unsigned _sp = 0; while (cond) { __builtin_amdgcn_s_sleep(1); \
;     if ((++_sp & 255u) == 0u) { if (xb_ld(&(bar)[XB_TMO])) break; if (_sp > XB_SPIN_CAP) { atomicAdd(&(bar)[XB_TMO], 1u); break; } } } } while (0)
; __device__ __forceinline__ void xcd_barrier(const XcdBarrier& b) {
;     ...
;             else XB_SPIN(xb_ld(&bar[XB_TOPGEN]) == tg, bar);
;             __builtin_amdgcn_fence(__ATOMIC_ACQUIRE, "agent");
;             xb_add(&bar[XB_XGEN(b.x)], 1u);
;             asm volatile("s_waitcnt vmcnt(0)" ::: "memory");
;         } else {
;             XB_SPIN(xb_ld(&bar[XB_XGEN(b.x)]) == gen, bar);
.LBB11_1692:
	s_and_b32 s13, s1, 0xff
	s_mov_b64 s[20:21], -1
	s_cmp_lg_u32 s13, 0
	s_mov_b64 s[24:25], -1
	s_nop 0
	s_cbranch_scc1 .LBB11_1695
	v_readlane_b32 s22, v249, 43
	v_readlane_b32 s23, v249, 44
	s_nop 4
	global_load_dword v2, v3, s[22:23] sc1
	s_waitcnt vmcnt(0)
	v_cmp_eq_u32_e32 vcc, 0, v2
	s_cbranch_vccnz .LBB11_1697
	s_mov_b64 s[24:25], 0
	s_mov_b64 s[22:23], -1

;     __device__ __forceinline__ bool run(const f32x4 (&v)[2][2][4][2], const Unit& u, int wr, int wc, int fr, int fq, PG8_LAS unsigned char* lds, int wid, int lane) const {
;     ...
;         if (wid == 0) {
;             bool dead = false; const unsigned long long t0 = __builtin_amdgcn_s_memrealtime(); const unsigned want = 8u * (unsigned)ntn;
;             for (;;) {
;                 if ((unsigned)__builtin_amdgcn_readfirstlane(__hip_atomic_load(cnt + 64 * u.pm, __ATOMIC_RELAXED, __HIP_MEMORY_SCOPE_AGENT)) >= want) break;
;                 if (__builtin_amdgcn_s_memrealtime() - t0 > 2000000ull) {
;                     if (lane == 0) { unsigned expect = 0u; __hip_atomic_compare_exchange_strong(tmo + 1, &expect, code | (unsigned)(u.pm & 0xff), __ATOMIC_RELAXED, __ATOMIC_RELAXED, __HIP_MEMORY_SCOPE_AGENT);
;                                      __hip_atomic_store(tmo, 1u, __ATOMIC_RELAXED, __HIP_MEMORY_SCOPE_AGENT); }
;                     dead = true; break; }
;                 __builtin_amdgcn_s_sleep(2);
;             }
.LBB11_2012:
	global_load_dword v2, v3, s[16:17] sc1
	s_mov_b64 s[18:19], -1
	s_mov_b64 s[20:21], -1
	s_waitcnt vmcnt(0)
	v_readfirstlane_b32 s1, v2
	s_cmp_gt_u32 s1, 63
	s_cbranch_scc1 .LBB11_2011
	s_memrealtime s[18:19]
	v_mov_b64_e32 v[136:137], 0x1e8481
	s_waitcnt lgkmcnt(0)
	s_sub_u32 s18, s18, s14
	s_subb_u32 s19, s19, s15
	v_cmp_lt_u64_e32 vcc, s[18:19], v[136:137]
	s_cbranch_vccz .LBB11_2010
	s_mov_b64 s[20:21], 0
	s_nop 0
	s_branch .LBB11_2010
